# q/k epilogue ssq cross-row reduction: ds_bpermute replaced by v_permlane16/32_swap + add (same addends, bit-identical), on top of full-line P6/P5/P4/P1-V epilogues
# speedup vs baseline: 1.0022x; 1.0022x over previous
.LBB0_169:
	v_pk_mul_f32 v[158:159], v[158:159], s[54:55] op_sel_hi:[1,0]
	v_pk_mul_f32 v[196:197], v[156:157], s[54:55] op_sel_hi:[1,0]
	v_pk_mul_f32 v[198:199], v[152:153], s[54:55] op_sel_hi:[1,0]
	v_mul_f32_e32 v152, v197, v197
	v_mul_f32_e32 v153, v159, v159
	v_fmac_f32_e32 v152, v196, v196
	v_fmac_f32_e32 v153, v158, v158
	v_and_b32_e32 v193, 64, v217
	v_add_f32_e32 v152, v152, v153
	v_mul_f32_e32 v153, v199, v199
	v_xor_b32_e32 v178, 16, v217
	v_add_u32_e32 v193, 64, v193
	v_pk_mul_f32 v[194:195], v[154:155], s[54:55] op_sel_hi:[1,0]
	v_fmac_f32_e32 v153, v198, v198
	v_cmp_lt_i32_e32 vcc, v178, v193
	v_add_f32_e32 v152, v152, v153
	v_mul_f32_e32 v153, v195, v195
	v_cndmask_b32_e32 v178, v217, v178, vcc
	v_fmac_f32_e32 v153, v194, v194
	v_lshlrev_b32_e32 v218, 2, v178
	v_add_f32_e32 v152, v153, v152
	v_mov_b32_e32 v153, v152
	s_nop 1
	v_permlane16_swap_b32 v153, v152
	s_nop 1
	v_xor_b32_e32 v178, 32, v217
	v_cmp_lt_i32_e32 vcc, v178, v193
	s_and_b64 s[76:77], s[74:75], exec
	v_ashrrev_i32_e32 v193, 31, v192
	v_cndmask_b32_e32 v178, v217, v178, vcc
	v_lshlrev_b32_e32 v219, 2, v178
	s_waitcnt lgkmcnt(0)
	v_add_f32_e32 v152, v152, v153
	v_mov_b32_e32 v153, v152
	s_nop 1
	v_permlane32_swap_b32 v153, v152
	s_nop 1
	s_cselect_b32 s76, 16, 0
	v_lshlrev_b64 v[156:157], 5, v[192:193]
	s_lshl_b32 s38, s70, 1
	v_or_b32_e32 v221, s76, v156
	s_and_b32 s65, s38, 14
	s_waitcnt vmcnt(0)
	s_and_saveexec_b64 s[70:71], s[6:7]
	s_cbranch_execz .LBB0_171
	v_or_b32_e32 v156, s65, v221
	s_waitcnt lgkmcnt(0)
	v_add_f32_e32 v154, v152, v153
	v_lshl_add_u64 v[152:153], v[156:157], 4, s[40:41]
	global_store_dword v[152:153], v154, off
.LBB0_171:
	s_or_b64 exec, exec, s[70:71]
	s_and_b64 s[70:71], s[74:75], exec
	s_mov_b32 s38, 0x8a00000
	s_cselect_b32 s38, s38, 0x8200000
	s_add_u32 s38, s30, s38
	s_addc_u32 s63, s31, 0
	s_lshl_b64 s[70:71], s[72:73], 1
	s_add_u32 s70, s38, s70
	s_addc_u32 s71, s63, s71
	v_lshlrev_b32_e32 v178, 1, v180
	v_mul_f32_e32 v156, v196, v0
	v_mul_f32_e32 v196, v159, v5
	s_waitcnt lgkmcnt(0)
	v_lshl_add_u64 v[152:153], s[70:71], 0, v[178:179]
	v_mul_f32_e32 v178, v197, v4
	v_mul_f32_e32 v158, v158, v1
	v_pk_mul_f32 v[196:197], v[196:197], v[166:167] op_sel:[0,1] op_sel_hi:[0,0]
	v_pk_mul_f32 v[226:227], v[178:179], v[164:165] op_sel:[0,1] op_sel_hi:[0,0]
	v_pk_fma_f32 v[230:231], v[158:159], v[166:167], v[196:197] neg_lo:[0,0,1] neg_hi:[0,0,1]
	v_pk_fma_f32 v[158:159], v[158:159], v[166:167], v[196:197] op_sel_hi:[0,1,1]
	v_pk_mul_f32 v[150:151], v[150:151], s[54:55] op_sel_hi:[1,0]
	v_pk_mul_f32 v[148:149], v[148:149], s[54:55] op_sel_hi:[1,0]
	v_pk_fma_f32 v[228:229], v[156:157], v[164:165], v[226:227] neg_lo:[0,0,1] neg_hi:[0,0,1]
	v_pk_fma_f32 v[226:227], v[156:157], v[164:165], v[226:227] op_sel_hi:[0,1,1]
	v_mul_f32_e32 v156, v149, v149
	v_mul_f32_e32 v158, v151, v151
	v_pk_mul_f32 v[144:145], v[144:145], s[54:55] op_sel_hi:[1,0]
	v_fmac_f32_e32 v156, v148, v148
	v_fmac_f32_e32 v158, v150, v150
	v_add_f32_e32 v156, v156, v158
	v_mul_f32_e32 v158, v145, v145
	v_pk_mul_f32 v[146:147], v[146:147], s[54:55] op_sel_hi:[1,0]
	v_fmac_f32_e32 v158, v144, v144
	v_add_f32_e32 v156, v156, v158
	v_mul_f32_e32 v158, v147, v147
	v_fmac_f32_e32 v158, v146, v146
	v_add_f32_e32 v156, v158, v156
	v_mov_b32_e32 v158, v156
	s_nop 1
	v_permlane16_swap_b32 v158, v156
	s_nop 1
	v_mul_f32_e32 v222, v199, v6
	v_mul_f32_e32 v198, v198, v2
	v_mul_f32_e32 v224, v195, v7
	v_pk_mul_f32 v[196:197], v[222:223], v[160:161] op_sel:[0,1] op_sel_hi:[0,0]
	s_waitcnt lgkmcnt(0)
	v_add_f32_e32 v156, v156, v158
	v_mov_b32_e32 v158, v156
	s_nop 1
	v_permlane32_swap_b32 v158, v156
	s_nop 1
	v_lshlrev_b64 v[154:155], 12, v[192:193]
	v_mul_f32_e32 v194, v194, v3
	v_pk_fma_f32 v[222:223], v[198:199], v[160:161], v[196:197] neg_lo:[0,0,1] neg_hi:[0,0,1]
	v_pk_fma_f32 v[196:197], v[198:199], v[160:161], v[196:197] op_sel_hi:[0,1,1]
	v_pk_mul_f32 v[198:199], v[224:225], v[162:163] op_sel:[0,1] op_sel_hi:[0,0]
	v_lshl_add_u64 v[154:155], v[152:153], 0, v[154:155]
	v_pk_fma_f32 v[224:225], v[194:195], v[162:163], v[198:199] neg_lo:[0,0,1] neg_hi:[0,0,1]
	v_pk_fma_f32 v[198:199], v[194:195], v[162:163], v[198:199] op_sel_hi:[0,1,1]
	s_lshl_b32 s38, s65, 8
	v_cvt_pk_bf16_f32 v194, v228, v227
	v_cvt_pk_bf16_f32 v195, v230, v159
	v_cvt_pk_bf16_f32 v196, v222, v197
	v_cvt_pk_bf16_f32 v197, v224, v199
	v_lshl_add_u64 v[198:199], v[154:155], 0, s[38:39]
	s_or_b32 s63, s65, 1
	global_store_dwordx4 v[198:199], v[194:197], off
	s_and_saveexec_b64 s[70:71], s[6:7]
	s_cbranch_execz .LBB0_173
	s_waitcnt lgkmcnt(0)
	v_add_f32_e32 v158, v156, v158
	v_or_b32_e32 v156, s63, v221
	v_lshl_add_u64 v[156:157], v[156:157], 4, s[40:41]
	global_store_dword v[156:157], v158, off
.LBB0_173:
	s_or_b64 exec, exec, s[70:71]
	v_pk_mov_b32 v[156:157], v[164:165], v[164:165] op_sel:[1,0]
	v_mul_f32_e32 v178, v149, v4
	s_waitcnt lgkmcnt(0)
	v_pk_mov_b32 v[158:159], v[166:167], v[166:167] op_sel:[1,0]
	v_mul_f32_e32 v148, v148, v0
	v_mul_f32_e32 v198, v151, v5
	v_pk_mul_f32 v[156:157], v[178:179], v[156:157] op_sel_hi:[0,1]
	v_pk_mov_b32 v[194:195], v[160:161], v[160:161] op_sel:[1,0]
	v_mul_f32_e32 v150, v150, v1
	v_mul_f32_e32 v222, v145, v6
	v_pk_fma_f32 v[226:227], v[148:149], v[164:165], v[156:157] neg_lo:[0,0,1] neg_hi:[0,0,1]
	v_pk_fma_f32 v[148:149], v[148:149], v[164:165], v[156:157] op_sel_hi:[0,1,1]
	v_pk_mul_f32 v[156:157], v[198:199], v[158:159] op_sel_hi:[0,1]
	v_mul_f32_e32 v144, v144, v2
	v_pk_fma_f32 v[158:159], v[150:151], v[166:167], v[156:157] neg_lo:[0,0,1] neg_hi:[0,0,1]
	v_pk_fma_f32 v[150:151], v[150:151], v[166:167], v[156:157] op_sel_hi:[0,1,1]
	v_pk_mul_f32 v[156:157], v[222:223], v[194:195] op_sel_hi:[0,1]
	v_pk_mov_b32 v[196:197], v[162:163], v[162:163] op_sel:[1,0]
	v_mul_f32_e32 v224, v147, v7
	v_pk_fma_f32 v[164:165], v[144:145], v[160:161], v[156:157] neg_lo:[0,0,1] neg_hi:[0,0,1]
	v_pk_fma_f32 v[144:145], v[144:145], v[160:161], v[156:157] op_sel_hi:[0,1,1]
	v_mul_f32_e32 v146, v146, v3
	v_pk_mul_f32 v[156:157], v[224:225], v[196:197] op_sel_hi:[0,1]
	v_cvt_pk_bf16_f32 v150, v164, v145
	v_pk_mul_f32 v[142:143], v[142:143], s[54:55] op_sel_hi:[1,0]
	v_pk_mul_f32 v[144:145], v[140:141], s[54:55] op_sel_hi:[1,0]
	v_pk_fma_f32 v[160:161], v[146:147], v[162:163], v[156:157] neg_lo:[0,0,1] neg_hi:[0,0,1]
	v_pk_fma_f32 v[156:157], v[146:147], v[162:163], v[156:157] op_sel_hi:[0,1,1]
	v_pk_mul_f32 v[146:147], v[136:137], s[54:55] op_sel_hi:[1,0]
	v_mul_f32_e32 v136, v145, v145
	v_mul_f32_e32 v137, v143, v143
	v_fmac_f32_e32 v136, v144, v144
	v_fmac_f32_e32 v137, v142, v142
	v_add_f32_e32 v136, v136, v137
	v_mul_f32_e32 v137, v147, v147
	v_pk_mul_f32 v[140:141], v[138:139], s[54:55] op_sel_hi:[1,0]
	v_fmac_f32_e32 v137, v146, v146
	v_add_f32_e32 v136, v136, v137
	v_mul_f32_e32 v137, v141, v141
	v_fmac_f32_e32 v137, v140, v140
	v_add_f32_e32 v138, v137, v136
	v_mov_b32_e32 v139, v138
	s_nop 1
	v_permlane16_swap_b32 v139, v138
	s_nop 1
	s_lshl_b32 s38, s63, 8
	v_cvt_pk_bf16_f32 v148, v226, v149
	v_cvt_pk_bf16_f32 v149, v158, v151
	v_cvt_pk_bf16_f32 v151, v160, v157
	v_lshl_add_u64 v[136:137], v[154:155], 0, s[38:39]
	global_store_dwordx4 v[136:137], v[148:151], off
	v_or_b32_e32 v136, 16, v192
	v_ashrrev_i32_e32 v137, 31, v136
	s_waitcnt lgkmcnt(0)
	v_add_f32_e32 v149, v138, v139
	v_mov_b32_e32 v150, v149
	s_nop 1
	v_permlane32_swap_b32 v150, v149
	s_nop 1
	v_lshlrev_b64 v[138:139], 5, v[136:137]
	v_or_b32_e32 v148, s76, v138
	s_and_saveexec_b64 s[70:71], s[6:7]
	s_cbranch_execz .LBB0_175
	v_or_b32_e32 v138, s65, v148
	s_waitcnt lgkmcnt(0)
	v_add_f32_e32 v149, v149, v150
	v_lshl_add_u64 v[150:151], v[138:139], 4, s[40:41]
	global_store_dword v[150:151], v149, off
.LBB0_175:
	s_or_b64 exec, exec, s[70:71]
	s_waitcnt lgkmcnt(0)
	v_mul_f32_e32 v150, v143, v5
	v_mul_f32_e32 v142, v142, v1
	v_mul_f32_e32 v154, v147, v6
	v_pk_mul_f32 v[150:151], v[150:151], v[30:31] op_sel:[0,1] op_sel_hi:[0,0]
	v_mul_f32_e32 v138, v144, v0
	v_mul_f32_e32 v144, v145, v4
	v_mul_f32_e32 v146, v146, v2
	v_mul_f32_e32 v156, v141, v7
	v_pk_fma_f32 v[160:161], v[142:143], v[30:31], v[150:151] neg_lo:[0,0,1] neg_hi:[0,0,1]
	v_pk_fma_f32 v[142:143], v[142:143], v[30:31], v[150:151] op_sel_hi:[0,1,1]
	v_pk_mul_f32 v[150:151], v[154:155], v[24:25] op_sel:[0,1] op_sel_hi:[0,0]
	s_lshl_b32 s38, s65, 7
	v_lshlrev_b64 v[136:137], 12, v[136:137]
	v_mul_f32_e32 v140, v140, v3
	v_pk_mul_f32 v[144:145], v[144:145], v[28:29] op_sel:[0,1] op_sel_hi:[0,0]
	v_pk_fma_f32 v[154:155], v[146:147], v[24:25], v[150:151] neg_lo:[0,0,1] neg_hi:[0,0,1]
	v_pk_fma_f32 v[146:147], v[146:147], v[24:25], v[150:151] op_sel_hi:[0,1,1]
	v_pk_mul_f32 v[150:151], v[156:157], v[26:27] op_sel:[0,1] op_sel_hi:[0,0]
	v_lshl_add_u64 v[136:137], v[152:153], 0, v[136:137]
	v_pk_fma_f32 v[158:159], v[138:139], v[28:29], v[144:145] neg_lo:[0,0,1] neg_hi:[0,0,1]
	v_pk_fma_f32 v[144:145], v[138:139], v[28:29], v[144:145] op_sel_hi:[0,1,1]
	v_pk_fma_f32 v[156:157], v[140:141], v[26:27], v[150:151] neg_lo:[0,0,1] neg_hi:[0,0,1]
	v_pk_fma_f32 v[150:151], v[140:141], v[26:27], v[150:151] op_sel_hi:[0,1,1]
	s_lshl_b32 s38, s38, 1
	v_cvt_pk_bf16_f32 v140, v158, v145
	v_cvt_pk_bf16_f32 v141, v160, v143
	v_cvt_pk_bf16_f32 v142, v154, v147
	v_cvt_pk_bf16_f32 v143, v156, v151
	v_lshl_add_u64 v[144:145], v[136:137], 0, s[38:39]
	v_pk_mul_f32 v[134:135], v[134:135], s[54:55] op_sel_hi:[1,0]
	v_pk_mul_f32 v[132:133], v[132:133], s[54:55] op_sel_hi:[1,0]
	global_store_dwordx4 v[144:145], v[140:143], off
	v_mul_f32_e32 v138, v133, v133
	v_pk_mul_f32 v[128:129], v[128:129], s[54:55] op_sel_hi:[1,0]
	v_mul_f32_e32 v140, v135, v135
	v_fmac_f32_e32 v138, v132, v132
	v_fmac_f32_e32 v140, v134, v134
	v_add_f32_e32 v138, v138, v140
	v_mul_f32_e32 v140, v129, v129
	v_pk_mul_f32 v[130:131], v[130:131], s[54:55] op_sel_hi:[1,0]
	v_fmac_f32_e32 v140, v128, v128
	v_add_f32_e32 v138, v138, v140
	v_mul_f32_e32 v140, v131, v131
	v_fmac_f32_e32 v140, v130, v130
	v_add_f32_e32 v138, v140, v138
	v_mov_b32_e32 v140, v138
	s_nop 1
	v_permlane16_swap_b32 v140, v138
	s_nop 1
	s_waitcnt lgkmcnt(0)
	v_add_f32_e32 v138, v138, v140
	v_mov_b32_e32 v140, v138
	s_nop 1
	v_permlane32_swap_b32 v140, v138
	s_nop 1
	s_and_saveexec_b64 s[70:71], s[6:7]
	s_cbranch_execz .LBB0_177
	s_waitcnt lgkmcnt(0)
	v_add_f32_e32 v140, v138, v140
	v_or_b32_e32 v138, s63, v148
	v_lshl_add_u64 v[138:139], v[138:139], 4, s[40:41]
	global_store_dword v[138:139], v140, off
.LBB0_177:
	s_or_b64 exec, exec, s[70:71]
	v_pk_mov_b32 v[138:139], v[28:29], v[28:29] op_sel:[1,0]
	v_mul_f32_e32 v146, v133, v4
	s_waitcnt lgkmcnt(0)
	v_pk_mov_b32 v[140:141], v[30:31], v[30:31] op_sel:[1,0]
	v_mul_f32_e32 v132, v132, v0
	v_mul_f32_e32 v148, v135, v5
	v_pk_mul_f32 v[138:139], v[146:147], v[138:139] op_sel_hi:[0,1]
	v_pk_mov_b32 v[142:143], v[24:25], v[24:25] op_sel:[1,0]
	v_mul_f32_e32 v134, v134, v1
	v_mul_f32_e32 v150, v129, v6
	v_pk_fma_f32 v[146:147], v[132:133], v[28:29], v[138:139] neg_lo:[0,0,1] neg_hi:[0,0,1]
	v_pk_fma_f32 v[28:29], v[132:133], v[28:29], v[138:139] op_sel_hi:[0,1,1]
	v_pk_mul_f32 v[132:133], v[148:149], v[140:141] op_sel_hi:[0,1]
	v_pk_mov_b32 v[144:145], v[26:27], v[26:27] op_sel:[1,0]
	v_mul_f32_e32 v128, v128, v2
	v_mul_f32_e32 v154, v131, v7
	v_pk_fma_f32 v[138:139], v[134:135], v[30:31], v[132:133] neg_lo:[0,0,1] neg_hi:[0,0,1]
	v_pk_fma_f32 v[30:31], v[134:135], v[30:31], v[132:133] op_sel_hi:[0,1,1]
	v_pk_mul_f32 v[132:133], v[150:151], v[142:143] op_sel_hi:[0,1]
	v_mul_f32_e32 v130, v130, v3
	v_pk_fma_f32 v[134:135], v[128:129], v[24:25], v[132:133] neg_lo:[0,0,1] neg_hi:[0,0,1]
	v_pk_fma_f32 v[128:129], v[128:129], v[24:25], v[132:133] op_sel_hi:[0,1,1]
	v_pk_mul_f32 v[24:25], v[154:155], v[144:145] op_sel_hi:[0,1]
	v_pk_fma_f32 v[132:133], v[130:131], v[26:27], v[24:25] neg_lo:[0,0,1] neg_hi:[0,0,1]
	v_pk_fma_f32 v[26:27], v[130:131], v[26:27], v[24:25] op_sel_hi:[0,1,1]
	v_cvt_pk_bf16_f32 v24, v146, v29
	v_pk_mul_f32 v[28:29], v[126:127], s[54:55] op_sel_hi:[1,0]
	v_pk_mul_f32 v[124:125], v[124:125], s[54:55] op_sel_hi:[1,0]
	v_cvt_pk_bf16_f32 v25, v138, v31
	v_pk_mul_f32 v[30:31], v[122:123], s[54:55] op_sel_hi:[1,0]
	v_mul_f32_e32 v122, v125, v125
	v_mul_f32_e32 v123, v29, v29
	v_pk_mul_f32 v[120:121], v[120:121], s[54:55] op_sel_hi:[1,0]
	v_fmac_f32_e32 v122, v124, v124
	v_fmac_f32_e32 v123, v28, v28
	v_add_f32_e32 v122, v122, v123
	v_mul_f32_e32 v123, v121, v121
	v_fmac_f32_e32 v123, v120, v120
	v_add_f32_e32 v122, v122, v123
	v_mul_f32_e32 v123, v31, v31
	v_fmac_f32_e32 v123, v30, v30
	v_add_f32_e32 v126, v123, v122
	v_mov_b32_e32 v127, v126
	s_nop 1
	v_permlane16_swap_b32 v127, v126
	s_nop 1
	s_lshl_b32 s70, s63, 7
	s_lshl_b32 s70, s70, 1
	s_mov_b32 s71, s39
	v_cvt_pk_bf16_f32 v26, v134, v129
	v_cvt_pk_bf16_f32 v27, v132, v27
	v_lshl_add_u64 v[122:123], v[136:137], 0, s[70:71]
	global_store_dwordx4 v[122:123], v[24:27], off
	s_waitcnt lgkmcnt(0)
	v_add_f32_e32 v123, v126, v127
	v_mov_b32_e32 v126, v123
	s_nop 1
	v_permlane32_swap_b32 v126, v123
	s_nop 1
	v_or_b32_e32 v24, 32, v192
	v_ashrrev_i32_e32 v25, 31, v24
	v_lshlrev_b64 v[26:27], 5, v[24:25]
	v_or_b32_e32 v122, s76, v26
	s_and_saveexec_b64 s[72:73], s[6:7]
	s_cbranch_execz .LBB0_179
	v_or_b32_e32 v26, s65, v122
	s_waitcnt lgkmcnt(0)
	v_add_f32_e32 v123, v123, v126
	v_lshl_add_u64 v[126:127], v[26:27], 4, s[40:41]
	global_store_dword v[126:127], v123, off
.LBB0_179:
	s_or_b64 exec, exec, s[72:73]
	s_waitcnt lgkmcnt(0)
	v_mul_f32_e32 v126, v29, v5
	v_mul_f32_e32 v28, v28, v1
	v_mul_f32_e32 v128, v121, v6
	v_pk_mul_f32 v[126:127], v[126:127], v[22:23] op_sel:[0,1] op_sel_hi:[0,0]
	v_mul_f32_e32 v26, v124, v0
	v_mul_f32_e32 v124, v125, v4
	v_mul_f32_e32 v120, v120, v2
	v_mul_f32_e32 v130, v31, v7
	v_pk_fma_f32 v[134:135], v[28:29], v[22:23], v[126:127] neg_lo:[0,0,1] neg_hi:[0,0,1]
	v_pk_fma_f32 v[28:29], v[28:29], v[22:23], v[126:127] op_sel_hi:[0,1,1]
	v_pk_mul_f32 v[126:127], v[128:129], v[16:17] op_sel:[0,1] op_sel_hi:[0,0]
	v_lshlrev_b64 v[24:25], 12, v[24:25]
	v_mul_f32_e32 v30, v30, v3
	v_pk_mul_f32 v[124:125], v[124:125], v[20:21] op_sel:[0,1] op_sel_hi:[0,0]
	v_pk_fma_f32 v[128:129], v[120:121], v[16:17], v[126:127] neg_lo:[0,0,1] neg_hi:[0,0,1]
	v_pk_fma_f32 v[120:121], v[120:121], v[16:17], v[126:127] op_sel_hi:[0,1,1]
	v_pk_mul_f32 v[126:127], v[130:131], v[18:19] op_sel:[0,1] op_sel_hi:[0,0]
	v_lshl_add_u64 v[24:25], v[152:153], 0, v[24:25]
	v_pk_fma_f32 v[132:133], v[26:27], v[20:21], v[124:125] neg_lo:[0,0,1] neg_hi:[0,0,1]
	v_pk_fma_f32 v[124:125], v[26:27], v[20:21], v[124:125] op_sel_hi:[0,1,1]
	v_pk_fma_f32 v[130:131], v[30:31], v[18:19], v[126:127] neg_lo:[0,0,1] neg_hi:[0,0,1]
	v_pk_fma_f32 v[30:31], v[30:31], v[18:19], v[126:127] op_sel_hi:[0,1,1]
	v_cvt_pk_bf16_f32 v28, v132, v125
	v_cvt_pk_bf16_f32 v29, v134, v29
	v_cvt_pk_bf16_f32 v30, v128, v121
	v_cvt_pk_bf16_f32 v31, v130, v31
	v_lshl_add_u64 v[120:121], v[24:25], 0, s[38:39]
	global_store_dwordx4 v[120:121], v[28:31], off
	v_pk_mul_f32 v[116:117], v[116:117], s[54:55] op_sel_hi:[1,0]
	v_pk_mul_f32 v[112:113], v[112:113], s[54:55] op_sel_hi:[1,0]
	v_pk_mul_f32 v[28:29], v[118:119], s[54:55] op_sel_hi:[1,0]
	v_pk_mul_f32 v[30:31], v[114:115], s[54:55] op_sel_hi:[1,0]
	v_mul_f32_e32 v26, v117, v117
	v_mul_f32_e32 v114, v29, v29
	v_fmac_f32_e32 v26, v116, v116
	v_fmac_f32_e32 v114, v28, v28
	v_add_f32_e32 v26, v26, v114
	v_mul_f32_e32 v114, v113, v113
	v_fmac_f32_e32 v114, v112, v112
	v_add_f32_e32 v26, v26, v114
	v_mul_f32_e32 v114, v31, v31
	v_fmac_f32_e32 v114, v30, v30
	v_add_f32_e32 v26, v114, v26
	v_mov_b32_e32 v114, v26
	s_nop 1
	v_permlane16_swap_b32 v114, v26
	s_nop 1
	s_waitcnt lgkmcnt(0)
	v_add_f32_e32 v26, v26, v114
	v_mov_b32_e32 v114, v26
	s_nop 1
	v_permlane32_swap_b32 v114, v26
	s_nop 1
	s_and_saveexec_b64 s[72:73], s[6:7]
	s_cbranch_execz .LBB0_181
	s_waitcnt lgkmcnt(0)
	v_add_f32_e32 v114, v26, v114
	v_or_b32_e32 v26, s63, v122
	v_lshl_add_u64 v[26:27], v[26:27], 4, s[40:41]
	global_store_dword v[26:27], v114, off
.LBB0_181:
	s_or_b64 exec, exec, s[72:73]
	v_pk_mov_b32 v[26:27], v[20:21], v[20:21] op_sel:[1,0]
	v_mul_f32_e32 v122, v117, v4
	s_waitcnt lgkmcnt(0)
	v_pk_mov_b32 v[114:115], v[22:23], v[22:23] op_sel:[1,0]
	v_mul_f32_e32 v116, v116, v0
	v_mul_f32_e32 v124, v29, v5
	v_pk_mul_f32 v[26:27], v[122:123], v[26:27] op_sel_hi:[0,1]
	v_pk_mov_b32 v[118:119], v[16:17], v[16:17] op_sel:[1,0]
	v_mul_f32_e32 v28, v28, v1
	v_mul_f32_e32 v126, v113, v6
	v_pk_fma_f32 v[122:123], v[116:117], v[20:21], v[26:27] neg_lo:[0,0,1] neg_hi:[0,0,1]
	v_pk_fma_f32 v[20:21], v[116:117], v[20:21], v[26:27] op_sel_hi:[0,1,1]
	v_pk_mul_f32 v[26:27], v[124:125], v[114:115] op_sel_hi:[0,1]
	v_pk_mov_b32 v[120:121], v[18:19], v[18:19] op_sel:[1,0]
	v_mul_f32_e32 v112, v112, v2
	v_mul_f32_e32 v128, v31, v7
	v_pk_fma_f32 v[114:115], v[28:29], v[22:23], v[26:27] neg_lo:[0,0,1] neg_hi:[0,0,1]
	v_pk_fma_f32 v[22:23], v[28:29], v[22:23], v[26:27] op_sel_hi:[0,1,1]
	v_pk_mul_f32 v[26:27], v[126:127], v[118:119] op_sel_hi:[0,1]
	v_mul_f32_e32 v30, v30, v3
	v_pk_fma_f32 v[28:29], v[112:113], v[16:17], v[26:27] neg_lo:[0,0,1] neg_hi:[0,0,1]
	v_pk_fma_f32 v[26:27], v[112:113], v[16:17], v[26:27] op_sel_hi:[0,1,1]
	v_pk_mul_f32 v[16:17], v[128:129], v[120:121] op_sel_hi:[0,1]
	v_pk_fma_f32 v[112:113], v[30:31], v[18:19], v[16:17] neg_lo:[0,0,1] neg_hi:[0,0,1]
	v_pk_fma_f32 v[18:19], v[30:31], v[18:19], v[16:17] op_sel_hi:[0,1,1]
	v_cvt_pk_bf16_f32 v16, v122, v21
	v_cvt_pk_bf16_f32 v18, v28, v27
	v_pk_mul_f32 v[20:21], v[110:111], s[54:55] op_sel_hi:[1,0]
	v_pk_mul_f32 v[26:27], v[108:109], s[54:55] op_sel_hi:[1,0]
	v_mul_f32_e32 v31, v21, v21
	v_mul_f32_e32 v30, v27, v27
	v_pk_mul_f32 v[28:29], v[104:105], s[54:55] op_sel_hi:[1,0]
	v_fmac_f32_e32 v30, v26, v26
	v_fmac_f32_e32 v31, v20, v20
	v_add_f32_e32 v30, v30, v31
	v_mul_f32_e32 v31, v29, v29
	v_cvt_pk_bf16_f32 v17, v114, v23
	v_pk_mul_f32 v[22:23], v[106:107], s[54:55] op_sel_hi:[1,0]
	v_fmac_f32_e32 v31, v28, v28
	v_add_f32_e32 v30, v30, v31
	v_mul_f32_e32 v31, v23, v23
	v_fmac_f32_e32 v31, v22, v22
	v_add_f32_e32 v30, v31, v30
	v_mov_b32_e32 v31, v30
	s_nop 1
	v_permlane16_swap_b32 v31, v30
	s_nop 1
	s_mov_b32 s71, s39
	v_cvt_pk_bf16_f32 v19, v112, v19
	v_lshl_add_u64 v[24:25], v[24:25], 0, s[70:71]
	global_store_dwordx4 v[24:25], v[16:19], off
	s_waitcnt lgkmcnt(0)
	v_add_f32_e32 v24, v30, v31
	v_mov_b32_e32 v25, v24
	s_nop 1
	v_permlane32_swap_b32 v25, v24
	s_nop 1
	v_or_b32_e32 v16, 48, v192
	v_ashrrev_i32_e32 v17, 31, v16
	v_lshlrev_b64 v[18:19], 5, v[16:17]
	v_or_b32_e32 v30, s76, v18
	s_and_saveexec_b64 s[72:73], s[6:7]
	s_cbranch_execz .LBB0_183
	v_or_b32_e32 v18, s65, v30
	s_waitcnt lgkmcnt(0)
	v_add_f32_e32 v31, v24, v25
	v_lshl_add_u64 v[24:25], v[18:19], 4, s[40:41]
	global_store_dword v[24:25], v31, off
.LBB0_183:
	s_or_b64 exec, exec, s[72:73]
	v_mul_f32_e32 v18, v26, v0
	v_mul_f32_e32 v26, v21, v5
	v_mul_f32_e32 v24, v27, v4
	v_mul_f32_e32 v20, v20, v1
	v_mul_f32_e32 v104, v29, v6
	v_pk_mul_f32 v[26:27], v[26:27], v[14:15] op_sel:[0,1] op_sel_hi:[0,0]
	v_mul_f32_e32 v28, v28, v2
	v_mul_f32_e32 v106, v23, v7
	v_pk_fma_f32 v[110:111], v[20:21], v[14:15], v[26:27] neg_lo:[0,0,1] neg_hi:[0,0,1]
	v_pk_fma_f32 v[20:21], v[20:21], v[14:15], v[26:27] op_sel_hi:[0,1,1]
	v_pk_mul_f32 v[26:27], v[104:105], v[8:9] op_sel:[0,1] op_sel_hi:[0,0]
	v_lshlrev_b64 v[16:17], 12, v[16:17]
	v_mul_f32_e32 v22, v22, v3
	s_waitcnt lgkmcnt(0)
	v_pk_mul_f32 v[24:25], v[24:25], v[12:13] op_sel:[0,1] op_sel_hi:[0,0]
	v_pk_fma_f32 v[104:105], v[28:29], v[8:9], v[26:27] neg_lo:[0,0,1] neg_hi:[0,0,1]
	v_pk_fma_f32 v[26:27], v[28:29], v[8:9], v[26:27] op_sel_hi:[0,1,1]
	v_pk_mul_f32 v[28:29], v[106:107], v[10:11] op_sel:[0,1] op_sel_hi:[0,0]
	v_lshl_add_u64 v[16:17], v[152:153], 0, v[16:17]
	v_pk_fma_f32 v[108:109], v[18:19], v[12:13], v[24:25] neg_lo:[0,0,1] neg_hi:[0,0,1]
	v_pk_fma_f32 v[24:25], v[18:19], v[12:13], v[24:25] op_sel_hi:[0,1,1]
	v_pk_fma_f32 v[106:107], v[22:23], v[10:11], v[28:29] neg_lo:[0,0,1] neg_hi:[0,0,1]
	v_pk_fma_f32 v[22:23], v[22:23], v[10:11], v[28:29] op_sel_hi:[0,1,1]
	v_cvt_pk_bf16_f32 v20, v108, v25
	v_cvt_pk_bf16_f32 v21, v110, v21
	v_cvt_pk_bf16_f32 v22, v104, v27
	v_cvt_pk_bf16_f32 v23, v106, v23
	v_lshl_add_u64 v[24:25], v[16:17], 0, s[38:39]
	global_store_dwordx4 v[24:25], v[20:23], off
	v_pk_mul_f32 v[24:25], v[100:101], s[54:55] op_sel_hi:[1,0]
	v_pk_mul_f32 v[26:27], v[96:97], s[54:55] op_sel_hi:[1,0]
	v_pk_mul_f32 v[20:21], v[102:103], s[54:55] op_sel_hi:[1,0]
	v_mul_f32_e32 v18, v25, v25
	v_mul_f32_e32 v28, v21, v21
	v_fmac_f32_e32 v18, v24, v24
	v_fmac_f32_e32 v28, v20, v20
	v_add_f32_e32 v18, v18, v28
	v_mul_f32_e32 v28, v27, v27
	v_pk_mul_f32 v[22:23], v[98:99], s[54:55] op_sel_hi:[1,0]
	v_fmac_f32_e32 v28, v26, v26
	v_add_f32_e32 v18, v18, v28
	v_mul_f32_e32 v28, v23, v23
	v_fmac_f32_e32 v28, v22, v22
	v_add_f32_e32 v18, v28, v18
	v_mov_b32_e32 v28, v18
	s_nop 1
	v_permlane16_swap_b32 v28, v18
	s_nop 1
	s_waitcnt lgkmcnt(0)
	v_add_f32_e32 v18, v18, v28
	v_mov_b32_e32 v28, v18
	s_nop 1
	v_permlane32_swap_b32 v28, v18
	s_nop 1
	s_and_saveexec_b64 s[72:73], s[6:7]
	s_cbranch_execz .LBB0_185
	s_waitcnt lgkmcnt(0)
	v_add_f32_e32 v28, v18, v28
	v_or_b32_e32 v18, s63, v30
	v_lshl_add_u64 v[18:19], v[18:19], 4, s[40:41]
	global_store_dword v[18:19], v28, off

.LBB0_193:
	v_pk_mul_f32 v[94:95], v[94:95], s[54:55] op_sel_hi:[1,0]
	v_pk_mul_f32 v[104:105], v[92:93], s[54:55] op_sel_hi:[1,0]
	v_pk_mul_f32 v[106:107], v[88:89], s[54:55] op_sel_hi:[1,0]
	v_mul_f32_e32 v88, v105, v105
	v_mul_f32_e32 v89, v95, v95
	v_fmac_f32_e32 v88, v104, v104
	v_fmac_f32_e32 v89, v94, v94
	v_add_f32_e32 v88, v88, v89
	v_mul_f32_e32 v89, v107, v107
	v_pk_mul_f32 v[92:93], v[90:91], s[54:55] op_sel_hi:[1,0]
	v_fmac_f32_e32 v89, v106, v106
	v_add_f32_e32 v88, v88, v89
	v_mul_f32_e32 v89, v93, v93
	v_fmac_f32_e32 v89, v92, v92
	v_add_f32_e32 v88, v89, v88
	v_mov_b32_e32 v89, v88
	s_nop 1
	v_permlane16_swap_b32 v89, v88
	s_nop 1
	s_waitcnt lgkmcnt(0)
	v_add_f32_e32 v109, v88, v89
	v_mov_b32_e32 v110, v109
	s_nop 1
	v_permlane32_swap_b32 v110, v109
	s_nop 1
	v_add_u32_e32 v88, 0x80, v192
	v_ashrrev_i32_e32 v89, 31, v88
	v_lshlrev_b64 v[90:91], 5, v[88:89]
	v_or_b32_e32 v108, s76, v90
	s_waitcnt vmcnt(0)
	s_and_saveexec_b64 s[10:11], s[6:7]
	s_cbranch_execz .LBB0_195
	v_or_b32_e32 v90, s65, v108
	s_waitcnt lgkmcnt(0)
	v_add_f32_e32 v109, v109, v110
	v_lshl_add_u64 v[110:111], v[90:91], 4, s[40:41]
	global_store_dword v[110:111], v109, off
.LBB0_195:
	s_or_b64 exec, exec, s[10:11]
	s_waitcnt lgkmcnt(0)
	v_mul_f32_e32 v110, v95, v5
	v_mul_f32_e32 v94, v94, v1
	v_mul_f32_e32 v112, v107, v6
	v_pk_mul_f32 v[110:111], v[110:111], v[102:103] op_sel:[0,1] op_sel_hi:[0,0]
	v_mul_f32_e32 v90, v104, v0
	v_mul_f32_e32 v104, v105, v4
	v_mul_f32_e32 v106, v106, v2
	v_mul_f32_e32 v114, v93, v7
	v_pk_fma_f32 v[118:119], v[94:95], v[102:103], v[110:111] neg_lo:[0,0,1] neg_hi:[0,0,1]
	v_pk_fma_f32 v[94:95], v[94:95], v[102:103], v[110:111] op_sel_hi:[0,1,1]
	v_pk_mul_f32 v[110:111], v[112:113], v[96:97] op_sel:[0,1] op_sel_hi:[0,0]
	v_lshlrev_b64 v[88:89], 12, v[88:89]
	v_mul_f32_e32 v92, v92, v3
	v_pk_mul_f32 v[104:105], v[104:105], v[100:101] op_sel:[0,1] op_sel_hi:[0,0]
	v_pk_fma_f32 v[112:113], v[106:107], v[96:97], v[110:111] neg_lo:[0,0,1] neg_hi:[0,0,1]
	v_pk_fma_f32 v[106:107], v[106:107], v[96:97], v[110:111] op_sel_hi:[0,1,1]
	v_pk_mul_f32 v[110:111], v[114:115], v[98:99] op_sel:[0,1] op_sel_hi:[0,0]
	v_lshl_add_u64 v[88:89], v[152:153], 0, v[88:89]
	v_pk_fma_f32 v[116:117], v[90:91], v[100:101], v[104:105] neg_lo:[0,0,1] neg_hi:[0,0,1]
	v_pk_fma_f32 v[104:105], v[90:91], v[100:101], v[104:105] op_sel_hi:[0,1,1]
	v_pk_fma_f32 v[114:115], v[92:93], v[98:99], v[110:111] neg_lo:[0,0,1] neg_hi:[0,0,1]
	v_pk_fma_f32 v[110:111], v[92:93], v[98:99], v[110:111] op_sel_hi:[0,1,1]
	v_cvt_pk_bf16_f32 v92, v116, v105
	v_cvt_pk_bf16_f32 v93, v118, v95
	v_cvt_pk_bf16_f32 v94, v112, v107
	v_cvt_pk_bf16_f32 v95, v114, v111
	v_lshl_add_u64 v[104:105], v[88:89], 0, s[38:39]
	v_pk_mul_f32 v[86:87], v[86:87], s[54:55] op_sel_hi:[1,0]
	v_pk_mul_f32 v[84:85], v[84:85], s[54:55] op_sel_hi:[1,0]
	global_store_dwordx4 v[104:105], v[92:95], off
	v_mul_f32_e32 v90, v85, v85
	v_pk_mul_f32 v[80:81], v[80:81], s[54:55] op_sel_hi:[1,0]
	v_mul_f32_e32 v92, v87, v87
	v_fmac_f32_e32 v90, v84, v84
	v_fmac_f32_e32 v92, v86, v86
	v_add_f32_e32 v90, v90, v92
	v_mul_f32_e32 v92, v81, v81
	v_pk_mul_f32 v[82:83], v[82:83], s[54:55] op_sel_hi:[1,0]
	v_fmac_f32_e32 v92, v80, v80
	v_add_f32_e32 v90, v90, v92
	v_mul_f32_e32 v92, v83, v83
	v_fmac_f32_e32 v92, v82, v82
	v_add_f32_e32 v90, v92, v90
	v_mov_b32_e32 v92, v90
	s_nop 1
	v_permlane16_swap_b32 v92, v90
	s_nop 1
	s_waitcnt lgkmcnt(0)
	v_add_f32_e32 v90, v90, v92
	v_mov_b32_e32 v92, v90
	s_nop 1
	v_permlane32_swap_b32 v92, v90
	s_nop 1
	s_and_saveexec_b64 s[10:11], s[6:7]
	s_cbranch_execz .LBB0_197
	s_waitcnt lgkmcnt(0)
	v_add_f32_e32 v92, v90, v92
	v_or_b32_e32 v90, s63, v108
	v_lshl_add_u64 v[90:91], v[90:91], 4, s[40:41]
	global_store_dword v[90:91], v92, off
.LBB0_197:
	s_or_b64 exec, exec, s[10:11]
	v_pk_mov_b32 v[90:91], v[100:101], v[100:101] op_sel:[1,0]
	v_mul_f32_e32 v106, v85, v4
	s_waitcnt lgkmcnt(0)
	v_pk_mov_b32 v[92:93], v[102:103], v[102:103] op_sel:[1,0]
	v_mul_f32_e32 v84, v84, v0
	v_mul_f32_e32 v108, v87, v5
	v_pk_mul_f32 v[90:91], v[106:107], v[90:91] op_sel_hi:[0,1]
	v_pk_mov_b32 v[94:95], v[96:97], v[96:97] op_sel:[1,0]
	v_mul_f32_e32 v86, v86, v1
	v_mul_f32_e32 v110, v81, v6
	v_pk_fma_f32 v[106:107], v[84:85], v[100:101], v[90:91] neg_lo:[0,0,1] neg_hi:[0,0,1]
	v_pk_fma_f32 v[84:85], v[84:85], v[100:101], v[90:91] op_sel_hi:[0,1,1]
	v_pk_mul_f32 v[90:91], v[108:109], v[92:93] op_sel_hi:[0,1]
	v_mul_f32_e32 v80, v80, v2
	v_pk_fma_f32 v[92:93], v[86:87], v[102:103], v[90:91] neg_lo:[0,0,1] neg_hi:[0,0,1]
	v_pk_fma_f32 v[86:87], v[86:87], v[102:103], v[90:91] op_sel_hi:[0,1,1]
	v_pk_mul_f32 v[90:91], v[110:111], v[94:95] op_sel_hi:[0,1]
	v_pk_mov_b32 v[104:105], v[98:99], v[98:99] op_sel:[1,0]
	v_mul_f32_e32 v112, v83, v7
	v_pk_fma_f32 v[94:95], v[80:81], v[96:97], v[90:91] neg_lo:[0,0,1] neg_hi:[0,0,1]
	v_pk_fma_f32 v[80:81], v[80:81], v[96:97], v[90:91] op_sel_hi:[0,1,1]
	v_mul_f32_e32 v82, v82, v3
	v_pk_mul_f32 v[90:91], v[112:113], v[104:105] op_sel_hi:[0,1]
	v_cvt_pk_bf16_f32 v86, v94, v81
	v_pk_mul_f32 v[78:79], v[78:79], s[54:55] op_sel_hi:[1,0]
	v_pk_mul_f32 v[80:81], v[76:77], s[54:55] op_sel_hi:[1,0]
	v_pk_fma_f32 v[96:97], v[82:83], v[98:99], v[90:91] neg_lo:[0,0,1] neg_hi:[0,0,1]
	v_pk_fma_f32 v[90:91], v[82:83], v[98:99], v[90:91] op_sel_hi:[0,1,1]
	v_pk_mul_f32 v[82:83], v[72:73], s[54:55] op_sel_hi:[1,0]
	v_mul_f32_e32 v72, v81, v81
	v_mul_f32_e32 v73, v79, v79
	v_fmac_f32_e32 v72, v80, v80
	v_fmac_f32_e32 v73, v78, v78
	v_add_f32_e32 v72, v72, v73
	v_mul_f32_e32 v73, v83, v83
	v_pk_mul_f32 v[76:77], v[74:75], s[54:55] op_sel_hi:[1,0]
	v_fmac_f32_e32 v73, v82, v82
	v_add_f32_e32 v72, v72, v73
	v_mul_f32_e32 v73, v77, v77
	v_fmac_f32_e32 v73, v76, v76
	v_add_f32_e32 v74, v73, v72
	v_mov_b32_e32 v75, v74
	s_nop 1
	v_permlane16_swap_b32 v75, v74
	s_nop 1
	s_mov_b32 s71, s39
	v_cvt_pk_bf16_f32 v84, v106, v85
	v_cvt_pk_bf16_f32 v85, v92, v87
	v_cvt_pk_bf16_f32 v87, v96, v91
	v_lshl_add_u64 v[72:73], v[88:89], 0, s[70:71]
	global_store_dwordx4 v[72:73], v[84:87], off
	v_add_u32_e32 v72, 0x90, v192
	v_ashrrev_i32_e32 v73, 31, v72
	s_waitcnt lgkmcnt(0)
	v_add_f32_e32 v85, v74, v75
	v_mov_b32_e32 v86, v85
	s_nop 1
	v_permlane32_swap_b32 v86, v85
	s_nop 1
	v_lshlrev_b64 v[74:75], 5, v[72:73]
	v_or_b32_e32 v84, s76, v74
	s_and_saveexec_b64 s[10:11], s[6:7]
	s_cbranch_execz .LBB0_199
	v_or_b32_e32 v74, s65, v84
	s_waitcnt lgkmcnt(0)
	v_add_f32_e32 v85, v85, v86
	v_lshl_add_u64 v[86:87], v[74:75], 4, s[40:41]
	global_store_dword v[86:87], v85, off
.LBB0_199:
	s_or_b64 exec, exec, s[10:11]
	s_waitcnt lgkmcnt(0)
	v_mul_f32_e32 v86, v79, v5
	v_mul_f32_e32 v78, v78, v1
	v_mul_f32_e32 v88, v83, v6
	v_pk_mul_f32 v[86:87], v[86:87], v[30:31] op_sel:[0,1] op_sel_hi:[0,0]
	v_mul_f32_e32 v74, v80, v0
	v_mul_f32_e32 v80, v81, v4
	v_mul_f32_e32 v82, v82, v2
	v_mul_f32_e32 v90, v77, v7
	v_pk_fma_f32 v[94:95], v[78:79], v[30:31], v[86:87] neg_lo:[0,0,1] neg_hi:[0,0,1]
	v_pk_fma_f32 v[78:79], v[78:79], v[30:31], v[86:87] op_sel_hi:[0,1,1]
	v_pk_mul_f32 v[86:87], v[88:89], v[24:25] op_sel:[0,1] op_sel_hi:[0,0]
	v_lshlrev_b64 v[72:73], 12, v[72:73]
	v_mul_f32_e32 v76, v76, v3
	v_pk_mul_f32 v[80:81], v[80:81], v[28:29] op_sel:[0,1] op_sel_hi:[0,0]
	v_pk_fma_f32 v[88:89], v[82:83], v[24:25], v[86:87] neg_lo:[0,0,1] neg_hi:[0,0,1]
	v_pk_fma_f32 v[82:83], v[82:83], v[24:25], v[86:87] op_sel_hi:[0,1,1]
	v_pk_mul_f32 v[86:87], v[90:91], v[26:27] op_sel:[0,1] op_sel_hi:[0,0]
	v_lshl_add_u64 v[72:73], v[152:153], 0, v[72:73]
	v_pk_fma_f32 v[92:93], v[74:75], v[28:29], v[80:81] neg_lo:[0,0,1] neg_hi:[0,0,1]
	v_pk_fma_f32 v[80:81], v[74:75], v[28:29], v[80:81] op_sel_hi:[0,1,1]
	v_pk_fma_f32 v[90:91], v[76:77], v[26:27], v[86:87] neg_lo:[0,0,1] neg_hi:[0,0,1]
	v_pk_fma_f32 v[86:87], v[76:77], v[26:27], v[86:87] op_sel_hi:[0,1,1]
	v_cvt_pk_bf16_f32 v76, v92, v81
	v_cvt_pk_bf16_f32 v77, v94, v79
	v_cvt_pk_bf16_f32 v78, v88, v83
	v_cvt_pk_bf16_f32 v79, v90, v87
	v_lshl_add_u64 v[80:81], v[72:73], 0, s[38:39]
	v_pk_mul_f32 v[70:71], v[70:71], s[54:55] op_sel_hi:[1,0]
	v_pk_mul_f32 v[68:69], v[68:69], s[54:55] op_sel_hi:[1,0]
	global_store_dwordx4 v[80:81], v[76:79], off
	v_mul_f32_e32 v74, v69, v69
	v_pk_mul_f32 v[64:65], v[64:65], s[54:55] op_sel_hi:[1,0]
	v_mul_f32_e32 v76, v71, v71
	v_fmac_f32_e32 v74, v68, v68
	v_fmac_f32_e32 v76, v70, v70
	v_add_f32_e32 v74, v74, v76
	v_mul_f32_e32 v76, v65, v65
	v_pk_mul_f32 v[66:67], v[66:67], s[54:55] op_sel_hi:[1,0]
	v_fmac_f32_e32 v76, v64, v64
	v_add_f32_e32 v74, v74, v76
	v_mul_f32_e32 v76, v67, v67
	v_fmac_f32_e32 v76, v66, v66
	v_add_f32_e32 v74, v76, v74
	v_mov_b32_e32 v76, v74
	s_nop 1
	v_permlane16_swap_b32 v76, v74
	s_nop 1
	s_waitcnt lgkmcnt(0)
	v_add_f32_e32 v74, v74, v76
	v_mov_b32_e32 v76, v74
	s_nop 1
	v_permlane32_swap_b32 v76, v74
	s_nop 1
	s_and_saveexec_b64 s[10:11], s[6:7]
	s_cbranch_execz .LBB0_201
	s_waitcnt lgkmcnt(0)
	v_add_f32_e32 v76, v74, v76
	v_or_b32_e32 v74, s63, v84
	v_lshl_add_u64 v[74:75], v[74:75], 4, s[40:41]
	global_store_dword v[74:75], v76, off
.LBB0_201:
	s_or_b64 exec, exec, s[10:11]
	v_pk_mov_b32 v[74:75], v[28:29], v[28:29] op_sel:[1,0]
	v_mul_f32_e32 v82, v69, v4
	s_waitcnt lgkmcnt(0)
	v_pk_mov_b32 v[76:77], v[30:31], v[30:31] op_sel:[1,0]
	v_mul_f32_e32 v68, v68, v0
	v_mul_f32_e32 v84, v71, v5
	v_pk_mul_f32 v[74:75], v[82:83], v[74:75] op_sel_hi:[0,1]
	v_pk_mov_b32 v[78:79], v[24:25], v[24:25] op_sel:[1,0]
	v_mul_f32_e32 v70, v70, v1
	v_mul_f32_e32 v86, v65, v6
	v_pk_fma_f32 v[82:83], v[68:69], v[28:29], v[74:75] neg_lo:[0,0,1] neg_hi:[0,0,1]
	v_pk_fma_f32 v[28:29], v[68:69], v[28:29], v[74:75] op_sel_hi:[0,1,1]
	v_pk_mul_f32 v[68:69], v[84:85], v[76:77] op_sel_hi:[0,1]
	v_pk_mov_b32 v[80:81], v[26:27], v[26:27] op_sel:[1,0]
	v_mul_f32_e32 v64, v64, v2
	v_mul_f32_e32 v88, v67, v7
	v_pk_fma_f32 v[74:75], v[70:71], v[30:31], v[68:69] neg_lo:[0,0,1] neg_hi:[0,0,1]
	v_pk_fma_f32 v[30:31], v[70:71], v[30:31], v[68:69] op_sel_hi:[0,1,1]
	v_pk_mul_f32 v[68:69], v[86:87], v[78:79] op_sel_hi:[0,1]
	v_mul_f32_e32 v66, v66, v3
	v_pk_fma_f32 v[70:71], v[64:65], v[24:25], v[68:69] neg_lo:[0,0,1] neg_hi:[0,0,1]
	v_pk_fma_f32 v[64:65], v[64:65], v[24:25], v[68:69] op_sel_hi:[0,1,1]
	v_pk_mul_f32 v[24:25], v[88:89], v[80:81] op_sel_hi:[0,1]
	v_pk_fma_f32 v[68:69], v[66:67], v[26:27], v[24:25] neg_lo:[0,0,1] neg_hi:[0,0,1]
	v_pk_fma_f32 v[26:27], v[66:67], v[26:27], v[24:25] op_sel_hi:[0,1,1]
	v_cvt_pk_bf16_f32 v24, v82, v29
	v_pk_mul_f32 v[28:29], v[62:63], s[54:55] op_sel_hi:[1,0]
	v_pk_mul_f32 v[60:61], v[60:61], s[54:55] op_sel_hi:[1,0]
	v_cvt_pk_bf16_f32 v25, v74, v31
	v_pk_mul_f32 v[30:31], v[58:59], s[54:55] op_sel_hi:[1,0]
	v_mul_f32_e32 v58, v61, v61
	v_mul_f32_e32 v59, v29, v29
	v_pk_mul_f32 v[56:57], v[56:57], s[54:55] op_sel_hi:[1,0]
	v_fmac_f32_e32 v58, v60, v60
	v_fmac_f32_e32 v59, v28, v28
	v_add_f32_e32 v58, v58, v59
	v_mul_f32_e32 v59, v57, v57
	v_fmac_f32_e32 v59, v56, v56
	v_add_f32_e32 v58, v58, v59
	v_mul_f32_e32 v59, v31, v31
	v_fmac_f32_e32 v59, v30, v30
	v_add_f32_e32 v62, v59, v58
	v_mov_b32_e32 v63, v62
	s_nop 1
	v_permlane16_swap_b32 v63, v62
	s_nop 1
	s_mov_b32 s71, s39
	v_cvt_pk_bf16_f32 v26, v70, v65
	v_cvt_pk_bf16_f32 v27, v68, v27
	v_lshl_add_u64 v[58:59], v[72:73], 0, s[70:71]
	global_store_dwordx4 v[58:59], v[24:27], off
	s_waitcnt lgkmcnt(0)
	v_add_f32_e32 v59, v62, v63
	v_mov_b32_e32 v62, v59
	s_nop 1
	v_permlane32_swap_b32 v62, v59
	s_nop 1
	v_add_u32_e32 v24, 0xa0, v192
	v_ashrrev_i32_e32 v25, 31, v24
	v_lshlrev_b64 v[26:27], 5, v[24:25]
	v_or_b32_e32 v58, s76, v26
	s_and_saveexec_b64 s[10:11], s[6:7]
	s_cbranch_execz .LBB0_203
	v_or_b32_e32 v26, s65, v58
	s_waitcnt lgkmcnt(0)
	v_add_f32_e32 v59, v59, v62
	v_lshl_add_u64 v[62:63], v[26:27], 4, s[40:41]
	global_store_dword v[62:63], v59, off
.LBB0_203:
	s_or_b64 exec, exec, s[10:11]
	s_waitcnt lgkmcnt(0)
	v_mul_f32_e32 v62, v29, v5
	v_mul_f32_e32 v28, v28, v1
	v_mul_f32_e32 v64, v57, v6
	v_pk_mul_f32 v[62:63], v[62:63], v[22:23] op_sel:[0,1] op_sel_hi:[0,0]
	v_mul_f32_e32 v26, v60, v0
	v_mul_f32_e32 v60, v61, v4
	v_mul_f32_e32 v56, v56, v2
	v_mul_f32_e32 v66, v31, v7
	v_pk_fma_f32 v[70:71], v[28:29], v[22:23], v[62:63] neg_lo:[0,0,1] neg_hi:[0,0,1]
	v_pk_fma_f32 v[28:29], v[28:29], v[22:23], v[62:63] op_sel_hi:[0,1,1]
	v_pk_mul_f32 v[62:63], v[64:65], v[16:17] op_sel:[0,1] op_sel_hi:[0,0]
	v_lshlrev_b64 v[24:25], 12, v[24:25]
	v_mul_f32_e32 v30, v30, v3
	v_pk_mul_f32 v[60:61], v[60:61], v[20:21] op_sel:[0,1] op_sel_hi:[0,0]
	v_pk_fma_f32 v[64:65], v[56:57], v[16:17], v[62:63] neg_lo:[0,0,1] neg_hi:[0,0,1]
	v_pk_fma_f32 v[56:57], v[56:57], v[16:17], v[62:63] op_sel_hi:[0,1,1]
	v_pk_mul_f32 v[62:63], v[66:67], v[18:19] op_sel:[0,1] op_sel_hi:[0,0]
	v_lshl_add_u64 v[24:25], v[152:153], 0, v[24:25]
	v_pk_fma_f32 v[68:69], v[26:27], v[20:21], v[60:61] neg_lo:[0,0,1] neg_hi:[0,0,1]
	v_pk_fma_f32 v[60:61], v[26:27], v[20:21], v[60:61] op_sel_hi:[0,1,1]
	v_pk_fma_f32 v[66:67], v[30:31], v[18:19], v[62:63] neg_lo:[0,0,1] neg_hi:[0,0,1]
	v_pk_fma_f32 v[30:31], v[30:31], v[18:19], v[62:63] op_sel_hi:[0,1,1]
	v_cvt_pk_bf16_f32 v28, v68, v61
	v_cvt_pk_bf16_f32 v29, v70, v29
	v_cvt_pk_bf16_f32 v30, v64, v57
	v_cvt_pk_bf16_f32 v31, v66, v31
	v_lshl_add_u64 v[56:57], v[24:25], 0, s[38:39]
	global_store_dwordx4 v[56:57], v[28:31], off
	v_pk_mul_f32 v[52:53], v[52:53], s[54:55] op_sel_hi:[1,0]
	v_pk_mul_f32 v[48:49], v[48:49], s[54:55] op_sel_hi:[1,0]
	v_pk_mul_f32 v[28:29], v[54:55], s[54:55] op_sel_hi:[1,0]
	v_pk_mul_f32 v[30:31], v[50:51], s[54:55] op_sel_hi:[1,0]
	v_mul_f32_e32 v26, v53, v53
	v_mul_f32_e32 v50, v29, v29
	v_fmac_f32_e32 v26, v52, v52
	v_fmac_f32_e32 v50, v28, v28
	v_add_f32_e32 v26, v26, v50
	v_mul_f32_e32 v50, v49, v49
	v_fmac_f32_e32 v50, v48, v48
	v_add_f32_e32 v26, v26, v50
	v_mul_f32_e32 v50, v31, v31
	v_fmac_f32_e32 v50, v30, v30
	v_add_f32_e32 v26, v50, v26
	v_mov_b32_e32 v50, v26
	s_nop 1
	v_permlane16_swap_b32 v50, v26
	s_nop 1
	s_waitcnt lgkmcnt(0)
	v_add_f32_e32 v26, v26, v50
	v_mov_b32_e32 v50, v26
	s_nop 1
	v_permlane32_swap_b32 v50, v26
	s_nop 1
	s_and_saveexec_b64 s[10:11], s[6:7]
	s_cbranch_execz .LBB0_205
	s_waitcnt lgkmcnt(0)
	v_add_f32_e32 v50, v26, v50
	v_or_b32_e32 v26, s63, v58
	v_lshl_add_u64 v[26:27], v[26:27], 4, s[40:41]
	global_store_dword v[26:27], v50, off
.LBB0_205:
	s_or_b64 exec, exec, s[10:11]
	v_pk_mov_b32 v[26:27], v[20:21], v[20:21] op_sel:[1,0]
	v_mul_f32_e32 v58, v53, v4
	s_waitcnt lgkmcnt(0)
	v_pk_mov_b32 v[50:51], v[22:23], v[22:23] op_sel:[1,0]
	v_mul_f32_e32 v52, v52, v0
	v_mul_f32_e32 v60, v29, v5
	v_pk_mul_f32 v[26:27], v[58:59], v[26:27] op_sel_hi:[0,1]
	v_pk_mov_b32 v[54:55], v[16:17], v[16:17] op_sel:[1,0]
	v_mul_f32_e32 v28, v28, v1
	v_mul_f32_e32 v62, v49, v6
	v_pk_fma_f32 v[58:59], v[52:53], v[20:21], v[26:27] neg_lo:[0,0,1] neg_hi:[0,0,1]
	v_pk_fma_f32 v[20:21], v[52:53], v[20:21], v[26:27] op_sel_hi:[0,1,1]
	v_pk_mul_f32 v[26:27], v[60:61], v[50:51] op_sel_hi:[0,1]
	v_pk_mov_b32 v[56:57], v[18:19], v[18:19] op_sel:[1,0]
	v_mul_f32_e32 v48, v48, v2
	v_mul_f32_e32 v64, v31, v7
	v_pk_fma_f32 v[50:51], v[28:29], v[22:23], v[26:27] neg_lo:[0,0,1] neg_hi:[0,0,1]
	v_pk_fma_f32 v[22:23], v[28:29], v[22:23], v[26:27] op_sel_hi:[0,1,1]
	v_pk_mul_f32 v[26:27], v[62:63], v[54:55] op_sel_hi:[0,1]
	v_mul_f32_e32 v30, v30, v3
	v_pk_fma_f32 v[28:29], v[48:49], v[16:17], v[26:27] neg_lo:[0,0,1] neg_hi:[0,0,1]
	v_pk_fma_f32 v[26:27], v[48:49], v[16:17], v[26:27] op_sel_hi:[0,1,1]
	v_pk_mul_f32 v[16:17], v[64:65], v[56:57] op_sel_hi:[0,1]
	v_pk_fma_f32 v[48:49], v[30:31], v[18:19], v[16:17] neg_lo:[0,0,1] neg_hi:[0,0,1]
	v_pk_fma_f32 v[18:19], v[30:31], v[18:19], v[16:17] op_sel_hi:[0,1,1]
	v_cvt_pk_bf16_f32 v16, v58, v21
	v_cvt_pk_bf16_f32 v18, v28, v27
	v_pk_mul_f32 v[20:21], v[46:47], s[54:55] op_sel_hi:[1,0]
	v_pk_mul_f32 v[26:27], v[44:45], s[54:55] op_sel_hi:[1,0]
	v_mul_f32_e32 v31, v21, v21
	v_mul_f32_e32 v30, v27, v27
	v_pk_mul_f32 v[28:29], v[40:41], s[54:55] op_sel_hi:[1,0]
	v_fmac_f32_e32 v30, v26, v26
	v_fmac_f32_e32 v31, v20, v20
	v_add_f32_e32 v30, v30, v31
	v_mul_f32_e32 v31, v29, v29
	v_cvt_pk_bf16_f32 v17, v50, v23
	v_pk_mul_f32 v[22:23], v[42:43], s[54:55] op_sel_hi:[1,0]
	v_fmac_f32_e32 v31, v28, v28
	v_add_f32_e32 v30, v30, v31
	v_mul_f32_e32 v31, v23, v23
	v_fmac_f32_e32 v31, v22, v22
	v_add_f32_e32 v30, v31, v30
	v_mov_b32_e32 v31, v30
	s_nop 1
	v_permlane16_swap_b32 v31, v30
	s_nop 1
	s_mov_b32 s71, s39
	v_cvt_pk_bf16_f32 v19, v48, v19
	v_lshl_add_u64 v[24:25], v[24:25], 0, s[70:71]
	global_store_dwordx4 v[24:25], v[16:19], off
	s_waitcnt lgkmcnt(0)
	v_add_f32_e32 v24, v30, v31
	v_mov_b32_e32 v25, v24
	s_nop 1
	v_permlane32_swap_b32 v25, v24
	s_nop 1
	v_add_u32_e32 v16, 0xb0, v192
	v_ashrrev_i32_e32 v17, 31, v16
	v_lshlrev_b64 v[18:19], 5, v[16:17]
	v_or_b32_e32 v30, s76, v18
	s_and_saveexec_b64 s[10:11], s[6:7]
	s_cbranch_execz .LBB0_207
	v_or_b32_e32 v18, s65, v30
	s_waitcnt lgkmcnt(0)
	v_add_f32_e32 v31, v24, v25
	v_lshl_add_u64 v[24:25], v[18:19], 4, s[40:41]
	global_store_dword v[24:25], v31, off
.LBB0_207:
	s_or_b64 exec, exec, s[10:11]
	v_mul_f32_e32 v18, v26, v0
	v_mul_f32_e32 v26, v21, v5
	v_mul_f32_e32 v24, v27, v4
	v_mul_f32_e32 v20, v20, v1
	v_mul_f32_e32 v40, v29, v6
	v_pk_mul_f32 v[26:27], v[26:27], v[14:15] op_sel:[0,1] op_sel_hi:[0,0]
	v_mul_f32_e32 v28, v28, v2
	v_mul_f32_e32 v42, v23, v7
	v_pk_fma_f32 v[46:47], v[20:21], v[14:15], v[26:27] neg_lo:[0,0,1] neg_hi:[0,0,1]
	v_pk_fma_f32 v[20:21], v[20:21], v[14:15], v[26:27] op_sel_hi:[0,1,1]
	v_pk_mul_f32 v[26:27], v[40:41], v[8:9] op_sel:[0,1] op_sel_hi:[0,0]
	v_lshlrev_b64 v[16:17], 12, v[16:17]
	v_mul_f32_e32 v22, v22, v3
	s_waitcnt lgkmcnt(0)
	v_pk_mul_f32 v[24:25], v[24:25], v[12:13] op_sel:[0,1] op_sel_hi:[0,0]
	v_pk_fma_f32 v[40:41], v[28:29], v[8:9], v[26:27] neg_lo:[0,0,1] neg_hi:[0,0,1]
	v_pk_fma_f32 v[26:27], v[28:29], v[8:9], v[26:27] op_sel_hi:[0,1,1]
	v_pk_mul_f32 v[28:29], v[42:43], v[10:11] op_sel:[0,1] op_sel_hi:[0,0]
	v_lshl_add_u64 v[16:17], v[152:153], 0, v[16:17]
	v_pk_fma_f32 v[44:45], v[18:19], v[12:13], v[24:25] neg_lo:[0,0,1] neg_hi:[0,0,1]
	v_pk_fma_f32 v[24:25], v[18:19], v[12:13], v[24:25] op_sel_hi:[0,1,1]
	v_pk_fma_f32 v[42:43], v[22:23], v[10:11], v[28:29] neg_lo:[0,0,1] neg_hi:[0,0,1]
	v_pk_fma_f32 v[22:23], v[22:23], v[10:11], v[28:29] op_sel_hi:[0,1,1]
	v_cvt_pk_bf16_f32 v20, v44, v25
	v_cvt_pk_bf16_f32 v21, v46, v21
	v_cvt_pk_bf16_f32 v22, v40, v27
	v_cvt_pk_bf16_f32 v23, v42, v23
	v_lshl_add_u64 v[24:25], v[16:17], 0, s[38:39]
	global_store_dwordx4 v[24:25], v[20:23], off
	v_pk_mul_f32 v[24:25], v[36:37], s[54:55] op_sel_hi:[1,0]
	v_pk_mul_f32 v[26:27], v[32:33], s[54:55] op_sel_hi:[1,0]
	v_pk_mul_f32 v[20:21], v[38:39], s[54:55] op_sel_hi:[1,0]
	v_mul_f32_e32 v18, v25, v25
	v_mul_f32_e32 v28, v21, v21
	v_fmac_f32_e32 v18, v24, v24
	v_fmac_f32_e32 v28, v20, v20
	v_add_f32_e32 v18, v18, v28
	v_mul_f32_e32 v28, v27, v27
	v_pk_mul_f32 v[22:23], v[34:35], s[54:55] op_sel_hi:[1,0]
	v_fmac_f32_e32 v28, v26, v26
	v_add_f32_e32 v18, v18, v28
	v_mul_f32_e32 v28, v23, v23
	v_fmac_f32_e32 v28, v22, v22
	v_add_f32_e32 v18, v28, v18
	v_mov_b32_e32 v28, v18
	s_nop 1
	v_permlane16_swap_b32 v28, v18
	s_nop 1
	s_waitcnt lgkmcnt(0)
	v_add_f32_e32 v18, v18, v28
	v_mov_b32_e32 v28, v18
	s_nop 1
	v_permlane32_swap_b32 v28, v18
	s_nop 1
	s_and_saveexec_b64 s[10:11], s[6:7]
	s_cbranch_execz .LBB0_209
	s_waitcnt lgkmcnt(0)
	v_add_f32_e32 v28, v18, v28
	v_or_b32_e32 v18, s63, v30
	v_lshl_add_u64 v[18:19], v[18:19], 4, s[40:41]
	global_store_dword v[18:19], v28, off
